# P0 gate/up weight-convert item remap: a workgroup's 8 items = 8 k-blocks x 1 n-block (128 B line reads, 512 B contiguous per output row written by one workgroup)
# speedup vs baseline: 1.0093x; 1.0093x over previous
.LBB0_48:
	s_andn2_b64 vcc, exec, s[4:5]
	s_cbranch_vccnz .LBB0_26
	s_mul_hi_i32 s0, s68, 0x2fa0be83
	s_lshr_b32 s4, s0, 31
	s_ashr_i32 s0, s0, 12
	s_add_i32 s0, s0, s4
	s_mul_i32 s4, s0, 0xffffaa00
	s_add_i32 s4, s68, s4
	s_ashr_i32 s5, s0, 1
	s_and_b32 s8, s0, 1
	s_cmp_eq_u32 s8, 0
	s_cselect_b32 s62, s52, s54
	s_mul_hi_i32 s63, s5, 0xac00000
	s_mul_i32 s5, s5, 0xac00000
	s_cselect_b32 s9, s53, s55
	s_add_u32 s5, s62, s5
	s_addc_u32 s63, s9, s63
	s_ashr_i32 s4, s4, 3
	s_mul_hi_i32 s9, s4, 0x2fa0be83
	s_lshr_b32 s62, s9, 31
	s_ashr_i32 s9, s9, 6
	s_add_i32 s62, s9, s62
	s_mul_i32 s9, s62, 0x158
	s_sub_i32 s9, s4, s9
	s_lshl_b32 s4, s9, 5
	s_mov_b32 s69, 0
	s_or_b32 s4, s4, s69
	s_cmp_lt_u32 s0, 2
	s_cselect_b32 s0, s61, 0xb000000
	s_add_u32 s0, s64, s0
	s_addc_u32 s69, s65, 0
	s_lshl_b32 s9, s9, 6
	s_and_b32 s9, s9, 0xffffff00
	s_and_b32 s70, s4, 0x60
	s_or_b32 s9, s9, s70
	s_lshl_b32 s8, s8, 7
	s_or_b32 s8, s9, s8
	s_ashr_i32 s9, s8, 31
	s_lshl_b64 s[8:9], s[8:9], 12
	s_add_u32 s0, s0, s8
	s_addc_u32 s8, s69, s9
	s_lshl_b32 s9, s62, 9
	s_and_b32 s62, s33, 0xe0
	s_lshl_b32 s62, s62, 1
	s_or_b32 s9, s9, s62
	s_ashr_i32 s62, s9, 31
	s_mul_i32 s70, s9, 0xac00
	s_mul_hi_i32 s69, s9, 0xac00
	s_add_u32 s70, s5, s70
	s_addc_u32 s63, s63, s69
	s_ashr_i32 s5, s4, 31
	s_lshl_b64 s[4:5], s[4:5], 2
	s_add_u32 s4, s70, s4
	s_addc_u32 s5, s63, s5
	s_add_u32 s70, s4, 0x15800
	s_addc_u32 s71, s5, 0
	global_load_dword v19, v33, s[4:5] nt
	global_load_dword v21, v33, s[70:71] nt
	s_add_u32 s70, s4, 0x2b000
	s_addc_u32 s71, s5, 0
	global_load_dword v23, v33, s[70:71] nt
	s_add_u32 s70, s4, 0x40800
	s_addc_u32 s71, s5, 0
	global_load_dword v25, v33, s[70:71] nt
	s_add_u32 s70, s4, 0x56000
	s_addc_u32 s71, s5, 0
	global_load_dword v42, v33, s[70:71] nt
	s_add_u32 s70, s4, 0x6b800
	s_addc_u32 s71, s5, 0
	global_load_dword v43, v33, s[70:71] nt
	s_add_u32 s70, s4, 0x81000
	s_addc_u32 s71, s5, 0
	global_load_dword v44, v33, s[70:71] nt
	s_add_u32 s70, s4, 0x96800
	s_addc_u32 s71, s5, 0
	global_load_dword v45, v33, s[70:71] nt
	s_add_u32 s70, s4, 0xac000
	s_addc_u32 s71, s5, 0
	global_load_dword v46, v33, s[70:71] nt
	s_add_u32 s70, s4, 0xc1800
	s_addc_u32 s71, s5, 0
	global_load_dword v47, v33, s[70:71] nt
	s_add_u32 s70, s4, 0xd7000
	s_addc_u32 s71, s5, 0
	global_load_dword v48, v33, s[70:71] nt
	s_add_u32 s70, s4, 0xec800
	s_addc_u32 s71, s5, 0
	global_load_dword v49, v33, s[70:71] nt
	s_add_u32 s70, s4, 0x102000
	s_addc_u32 s71, s5, 0
	global_load_dword v50, v33, s[70:71] nt
	s_add_u32 s70, s4, 0x117800
	s_addc_u32 s71, s5, 0
	global_load_dword v51, v33, s[70:71] nt
	s_add_u32 s70, s4, 0x12d000
	s_addc_u32 s71, s5, 0
	global_load_dword v52, v33, s[70:71] nt
	s_add_u32 s70, s4, 0x142800
	s_addc_u32 s71, s5, 0
	global_load_dword v53, v33, s[70:71] nt
	s_add_u32 s70, s4, 0x158000
	s_addc_u32 s71, s5, 0
	global_load_dword v54, v33, s[70:71] nt
	s_add_u32 s70, s4, 0x16d800
	s_addc_u32 s71, s5, 0
	global_load_dword v55, v33, s[70:71] nt
	s_add_u32 s70, s4, 0x183000
	s_addc_u32 s71, s5, 0
	global_load_dword v56, v33, s[70:71] nt
	s_add_u32 s70, s4, 0x198800
	s_addc_u32 s71, s5, 0
	global_load_dword v57, v33, s[70:71] nt
	s_add_u32 s70, s4, 0x1ae000
	s_addc_u32 s71, s5, 0
	global_load_dword v58, v33, s[70:71] nt
	s_add_u32 s70, s4, 0x1c3800
	s_addc_u32 s71, s5, 0
	global_load_dword v59, v33, s[70:71] nt
	s_add_u32 s70, s4, 0x1d9000
	s_addc_u32 s71, s5, 0
	global_load_dword v60, v33, s[70:71] nt
	s_add_u32 s70, s4, 0x1ee800
	s_addc_u32 s71, s5, 0
	global_load_dword v61, v33, s[70:71] nt
	s_add_u32 s70, s4, 0x204000
	s_addc_u32 s71, s5, 0
	global_load_dword v62, v33, s[70:71] nt
	s_add_u32 s70, s4, 0x219800
	s_addc_u32 s71, s5, 0
	global_load_dword v63, v33, s[70:71] nt
	s_add_u32 s70, s4, 0x22f000
	s_addc_u32 s71, s5, 0
	global_load_dword v64, v33, s[70:71] nt
	s_add_u32 s70, s4, 0x244800
	s_addc_u32 s71, s5, 0
	global_load_dword v65, v33, s[70:71] nt
	s_add_u32 s70, s4, 0x25a000
	s_addc_u32 s71, s5, 0
	global_load_dword v66, v33, s[70:71] nt
	s_add_u32 s70, s4, 0x26f800
	s_addc_u32 s71, s5, 0
	global_load_dword v67, v33, s[70:71] nt
	s_add_u32 s70, s4, 0x285000
	s_addc_u32 s71, s5, 0
	s_add_u32 s4, s4, 0x29a800
	global_load_dword v68, v33, s[70:71] nt
	s_addc_u32 s5, s5, 0
	global_load_dword v69, v33, s[4:5] nt
	s_waitcnt vmcnt(0)
	s_add_u32 s4, s0, s9
	ds_write2_b32 v30, v19, v21 offset1:66
	ds_write2_b32 v30, v23, v25 offset0:132 offset1:198
	ds_write2_b32 v34, v42, v43 offset0:8 offset1:74
	ds_write2_b32 v34, v44, v45 offset0:140 offset1:206
	ds_write2_b32 v35, v46, v47 offset0:16 offset1:82
	ds_write2_b32 v35, v48, v49 offset0:148 offset1:214
	ds_write2_b32 v36, v50, v51 offset0:24 offset1:90
	ds_write2_b32 v36, v52, v53 offset0:156 offset1:222
	ds_write2_b32 v37, v54, v55 offset0:32 offset1:98
	ds_write2_b32 v37, v56, v57 offset0:164 offset1:230
	ds_write2_b32 v38, v58, v59 offset0:40 offset1:106
	ds_write2_b32 v38, v60, v61 offset0:172 offset1:238
	ds_write2_b32 v39, v62, v63 offset0:48 offset1:114
	ds_write2_b32 v39, v64, v65 offset0:180 offset1:246
	ds_write2_b32 v40, v66, v67 offset0:56 offset1:122
	ds_write2_b32 v40, v68, v69 offset0:188 offset1:254
	s_waitcnt lgkmcnt(0)
	ds_read2_b32 v[48:49], v31 offset1:16
	ds_read2_b32 v[50:51], v31 offset0:33 offset1:49
	ds_read2_b32 v[52:53], v31 offset0:66 offset1:82
	ds_read2_b32 v[54:55], v31 offset0:99 offset1:115
	ds_read2_b32 v[56:57], v31 offset0:132 offset1:148
	ds_read2_b32 v[58:59], v31 offset0:165 offset1:181
	ds_read2_b32 v[60:61], v31 offset0:198 offset1:214
	ds_read2_b32 v[62:63], v31 offset0:231 offset1:247
	ds_read2_b32 v[64:65], v41 offset0:8 offset1:24
	ds_read2_b32 v[66:67], v41 offset0:41 offset1:57
	ds_read2_b32 v[68:69], v41 offset0:74 offset1:90
	ds_read2_b32 v[70:71], v41 offset0:107 offset1:123
	ds_read2_b32 v[72:73], v41 offset0:140 offset1:156
	ds_read2_b32 v[74:75], v41 offset0:173 offset1:189
	ds_read2_b32 v[76:77], v41 offset0:206 offset1:222
	ds_read2_b32 v[78:79], v41 offset0:239 offset1:255
	s_addc_u32 s5, s8, s62
	v_mov_b32_e32 v42, 0
	v_mov_b32_e32 v43, 0
	v_mov_b32_e32 v44, 0
	v_mov_b32_e32 v45, 0
	v_lshl_add_u64 v[46:47], s[4:5], 0, v[2:3]
	s_waitcnt lgkmcnt(14)
	v_cvt_scalef32_pk_fp8_f32 v42, v48, v50, s49
	s_waitcnt lgkmcnt(10)
	v_cvt_scalef32_pk_fp8_f32 v43, v56, v58, s49
	s_waitcnt lgkmcnt(6)
	v_cvt_scalef32_pk_fp8_f32 v44, v64, v66, s49
	s_waitcnt lgkmcnt(2)
	v_cvt_scalef32_pk_fp8_f32 v45, v72, v74, s49
	v_cvt_scalef32_pk_fp8_f32 v42, v52, v54, s49 op_sel:[0,0,0,1]
	v_cvt_scalef32_pk_fp8_f32 v43, v60, v62, s49 op_sel:[0,0,0,1]
	v_cvt_scalef32_pk_fp8_f32 v44, v68, v70, s49 op_sel:[0,0,0,1]
	s_waitcnt lgkmcnt(0)
	v_cvt_scalef32_pk_fp8_f32 v45, v76, v78, s49 op_sel:[0,0,0,1]
	v_lshl_add_u64 v[80:81], v[46:47], 0, v[4:5]
	global_store_dwordx4 v[80:81], v[42:45], off
	v_lshl_add_u64 v[46:47], v[46:47], 0, v[6:7]
	s_nop 0
	v_mov_b32_e32 v42, 0
	v_mov_b32_e32 v43, 0
	v_mov_b32_e32 v44, 0
	v_mov_b32_e32 v45, 0
	v_cvt_scalef32_pk_fp8_f32 v42, v49, v51, s49
	v_cvt_scalef32_pk_fp8_f32 v43, v57, v59, s49
	v_cvt_scalef32_pk_fp8_f32 v44, v65, v67, s49
	v_cvt_scalef32_pk_fp8_f32 v45, v73, v75, s49
	v_cvt_scalef32_pk_fp8_f32 v42, v53, v55, s49 op_sel:[0,0,0,1]
	v_cvt_scalef32_pk_fp8_f32 v43, v61, v63, s49 op_sel:[0,0,0,1]
	v_cvt_scalef32_pk_fp8_f32 v44, v69, v71, s49 op_sel:[0,0,0,1]
	v_cvt_scalef32_pk_fp8_f32 v45, v77, v79, s49 op_sel:[0,0,0,1]
	global_store_dwordx4 v[46:47], v[42:45], off
	s_waitcnt lgkmcnt(0)
	s_branch .LBB0_26
